# v30 + scan ticket prefetch (next short-unit ticket fetched one unit ahead into a spare VGPR; same 8-byte placement phase downstream)
# speedup vs baseline: 1.0015x; 1.0015x over previous
.LBB0_580:
	s_mov_b32 s16, 2
	s_and_b64 vcc, exec, s[78:79]
	s_cbranch_vccz .LBB0_589
	s_xor_b64 s[16:17], s[70:71], -1
	s_mov_b64 s[74:75], -1
	s_and_b64 vcc, exec, s[16:17]
	s_mov_b32 s17, s86
	s_mov_b64 s[76:77], s[24:25]
	s_mov_b64 s[46:47], -1
	s_cbranch_vccz .LBB0_590
	s_barrier
	s_and_saveexec_b64 s[46:47], s[4:5]
	s_cbranch_execz .LBB0_586
	s_mov_b64 s[74:75], exec
	v_mbcnt_lo_u32_b32 v0, s74, 0
	v_mbcnt_hi_u32_b32 v0, s75, v0
	v_cmp_eq_u32_e32 vcc, 0, v0
	s_and_saveexec_b64 s[70:71], vcc
	s_cbranch_execz .LBB0_585
	s_waitcnt vmcnt(0)
	v_mov_b32_e32 v2, v255
	v_mov_b32_e32 v255, 1
	v_readlane_b32 s16, v254, 52
	v_readlane_b32 s17, v254, 53
	s_nop 4
	global_atomic_add v255, v1, v255, s[16:17] sc0
	s_nop 0
